# attention: exact counted waits in all four PV windows (loop + peeled tail) plus K-fragment read hoist, over v31
# speedup vs baseline: 1.0078x; 1.0008x over previous
; __device__ __forceinline__ void finishSM(f32x16& p0, f32x16& p1, float alpha, float& l_reg, bf16x8& pa0, bf16x8& pa1, bf16x8& pa2, bf16x8& pa3) {
;   for (int r = 0; r < 16; ++r) p1[r] = __builtin_amdgcn_exp2f(p1[r]);
;   float ps = 0; for (int r = 0; r < 16; ++r) ps += p0[r]; for (int r = 0; r < 16; ++r) ps += p1[r];
;   { auto rr = __builtin_amdgcn_permlane32_swap(__float_as_uint(ps), __float_as_uint(ps), false, false);
;     ps = __uint_as_float(rr[0]) + __uint_as_float(rr[1]); }
;   l_reg = l_reg * alpha + ps;
;     ...
;   PK4(p0, 0, pa0); PK4(p0, 8, pa1); PK4(p1, 0, pa2); PK4(p1, 8, pa3);
;     ...
; }
; __device__ __forceinline__ void qkt(f32x16& p0, f32x16& p1, const bf16* Ks, const bf16x8* qr, int r32, int hi) {
;   p0 = f32x16{}; p1 = f32x16{};
;   for (int d0 = 0; d0 < 8; ++d0) { int cb = (d0 * 16 + hi * 8) * 2;
;     bf16x8 b0 = *reinterpret_cast<const bf16x8*>((const char*)Ks + KSWZ(r32, cb));
;     bf16x8 b1 = *reinterpret_cast<const bf16x8*>((const char*)Ks + KSWZ(32 + r32, cb));
;     p0 = __builtin_amdgcn_mfma_f32_32x32x16_bf16(b0, qr[d0], p0, 0, 0, 0);
;     p1 = __builtin_amdgcn_mfma_f32_32x32x16_bf16(b1, qr[d0], p1, 0, 0, 0); }
.LBB0_180:
	ds_read_b128 v[66:69], v212 offset:49152
	ds_read_b128 v[70:73], v212 offset:57344
	ds_read_b128 v[228:231], v217 offset:49152
	ds_read_b128 v[232:235], v217 offset:57344
	v_add_f32_e32 v162, 0, v163
	v_add_f32_e32 v162, v177, v162
	s_waitcnt lgkmcnt(3)
	v_mfma_f32_32x32x16_bf16 v[82:97], v[66:69], v[118:121], 0
	v_add_f32_e32 v162, v164, v162
	v_add_f32_e32 v162, v224, v162
	v_add_f32_e32 v162, v176, v162
	v_add_f32_e32 v162, v227, v162
	v_add_f32_e32 v162, v165, v162
	v_add_f32_e32 v162, v175, v162
	v_add_f32_e32 v162, v166, v162
	s_waitcnt lgkmcnt(2)
	v_mfma_f32_32x32x16_bf16 v[66:81], v[70:73], v[118:121], 0
	v_add_f32_e32 v162, v173, v162
	v_add_f32_e32 v162, v167, v162
	v_add_f32_e32 v162, v174, v162
	v_exp_f32_e32 v160, v160
	v_add_f32_e32 v162, v168, v162
	v_exp_f32_e32 v161, v161
	v_add_f32_e32 v162, v171, v162
	s_waitcnt lgkmcnt(1)
	v_mfma_f32_32x32x16_bf16 v[82:97], v[228:231], v[110:113], v[82:97]
	ds_read_b128 v[228:231], v216 offset:49152
	v_exp_f32_e32 v158, v158
	v_add_f32_e32 v162, v169, v162
	v_exp_f32_e32 v159, v159
	v_add_f32_e32 v162, v172, v162
	v_exp_f32_e32 v154, v154
	v_add_f32_e32 v162, v160, v162
	v_exp_f32_e32 v155, v155
	s_waitcnt lgkmcnt(1)
	v_mfma_f32_32x32x16_bf16 v[66:81], v[232:235], v[110:113], v[66:81]
	ds_read_b128 v[232:235], v216 offset:57344
	v_add_f32_e32 v162, v161, v162
	v_exp_f32_e32 v150, v150
	v_add_f32_e32 v162, v158, v162
	v_exp_f32_e32 v151, v151
	v_add_f32_e32 v162, v159, v162
	v_exp_f32_e32 v148, v148
	s_waitcnt lgkmcnt(1)
	v_mfma_f32_32x32x16_bf16 v[82:97], v[228:231], v[126:129], v[82:97]
	ds_read_b128 v[228:231], v215 offset:49152
	v_add_f32_e32 v162, v154, v162
	v_exp_f32_e32 v149, v149
	v_add_f32_e32 v162, v155, v162
	v_exp_f32_e32 v156, v156
	v_add_f32_e32 v162, v150, v162
	v_exp_f32_e32 v157, v157
	v_add_f32_e32 v162, v151, v162
	s_waitcnt lgkmcnt(1)
	v_mfma_f32_32x32x16_bf16 v[66:81], v[232:235], v[126:129], v[66:81]
	ds_read_b128 v[232:235], v215 offset:57344
	v_exp_f32_e32 v152, v152
	v_add_f32_e32 v162, v148, v162
	v_exp_f32_e32 v153, v153
	v_add_f32_e32 v162, v149, v162
	v_exp_f32_e32 v146, v146
	v_add_f32_e32 v162, v156, v162
	s_waitcnt lgkmcnt(1)
	v_mfma_f32_32x32x16_bf16 v[82:97], v[228:231], v[122:125], v[82:97]
	ds_read_b128 v[228:231], v213 offset:49152
	v_exp_f32_e32 v147, v147
	v_add_f32_e32 v162, v157, v162
	v_add_f32_e32 v162, v152, v162
	v_add_f32_e32 v162, v153, v162
	v_add_f32_e32 v162, v146, v162
	v_add_f32_e32 v221, v147, v162
	v_mov_b32_e32 v222, v221
	s_waitcnt lgkmcnt(1)
	v_mfma_f32_32x32x16_bf16 v[66:81], v[232:235], v[122:125], v[66:81]
	ds_read_b128 v[232:235], v213 offset:57344
	v_permlane32_swap_b32_e32 v221, v222
	s_waitcnt lgkmcnt(1)
	v_mfma_f32_32x32x16_bf16 v[82:97], v[228:231], v[114:117], v[82:97]
	ds_read_b128 v[228:231], v214 offset:49152
	s_waitcnt lgkmcnt(1)
	v_mfma_f32_32x32x16_bf16 v[66:81], v[232:235], v[114:117], v[66:81]
	ds_read_b128 v[232:235], v214 offset:57344
	s_waitcnt lgkmcnt(1)
	v_mfma_f32_32x32x16_bf16 v[82:97], v[228:231], v[106:109], v[82:97]
	ds_read_b128 v[228:231], v219 offset:49152
	s_waitcnt lgkmcnt(1)
	v_mfma_f32_32x32x16_bf16 v[66:81], v[232:235], v[106:109], v[66:81]
	ds_read_b128 v[232:235], v219 offset:57344
	s_waitcnt lgkmcnt(1)
	v_mfma_f32_32x32x16_bf16 v[82:97], v[228:231], v[102:105], v[82:97]
	ds_read_b128 v[228:231], v218 offset:49152
	s_waitcnt lgkmcnt(1)
	v_mfma_f32_32x32x16_bf16 v[66:81], v[232:235], v[102:105], v[66:81]
	ds_read_b128 v[232:235], v218 offset:57344
	v_cvt_pk_bf16_f32 v162, v163, v177
	v_cvt_pk_bf16_f32 v163, v164, v224
	v_cvt_pk_bf16_f32 v164, v176, v227
	v_cvt_pk_bf16_f32 v165, v165, v175
	v_cvt_pk_bf16_f32 v166, v166, v173
	v_cvt_pk_bf16_f32 v167, v167, v174
	s_waitcnt lgkmcnt(1)
	v_mfma_f32_32x32x16_bf16 v[82:97], v[228:231], v[98:101], v[82:97]
	v_permlane32_swap_b32_e32 v162, v164
	v_cvt_pk_bf16_f32 v168, v168, v171
	v_cvt_pk_bf16_f32 v169, v169, v172
	v_cvt_pk_bf16_f32 v172, v160, v161
	v_cvt_pk_bf16_f32 v173, v158, v159
	v_cvt_pk_bf16_f32 v174, v154, v155
	s_waitcnt lgkmcnt(0)
	v_mfma_f32_32x32x16_bf16 v[66:81], v[232:235], v[98:101], v[66:81]
	v_cvt_pk_bf16_f32 v175, v150, v151
	v_cvt_pk_bf16_f32 v224, v148, v149
	v_cvt_pk_bf16_f32 v225, v156, v157
	v_cvt_pk_bf16_f32 v226, v152, v153
	v_cvt_pk_bf16_f32 v227, v146, v147
	v_permlane32_swap_b32_e32 v163, v165
	v_permlane32_swap_b32_e32 v166, v168
	v_permlane32_swap_b32_e32 v167, v169
	v_permlane32_swap_b32_e32 v172, v174
	v_permlane32_swap_b32_e32 v173, v175
	v_permlane32_swap_b32_e32 v224, v226
	v_permlane32_swap_b32_e32 v225, v227
	s_movk_i32 s0, 0xa000
	v_add_co_u32_e32 v146, vcc, s0, v182
	s_movk_i32 s0, 0xc000
	s_nop 0
	v_addc_co_u32_e32 v147, vcc, -1, v183, vcc
	v_add_co_u32_e32 v150, vcc, s0, v182
	s_mov_b32 s0, 0xfeefa000
	s_nop 0
	v_addc_co_u32_e32 v151, vcc, -1, v183, vcc
	v_add_co_u32_e32 v154, vcc, s0, v182
	s_mov_b32 s0, 0xfeefc000
	s_nop 0
	v_addc_co_u32_e32 v155, vcc, -1, v183, vcc
	v_add_co_u32_e32 v158, vcc, s0, v182
	global_load_dwordx4 v[146:149], v[146:147], off
	s_nop 0
	global_load_dwordx4 v[150:153], v[150:151], off
	v_addc_co_u32_e32 v159, vcc, -1, v183, vcc
	global_load_dwordx4 v[154:157], v[154:155], off
	s_nop 0
	global_load_dwordx4 v[158:161], v[158:159], off
	ds_read_b64_tr_b16 v[228:229], v207 offset:0
	ds_read_b64_tr_b16 v[230:231], v207 offset:0x800
	ds_read_b64_tr_b16 v[232:233], v207 offset:0x1000
	ds_read_b64_tr_b16 v[234:235], v207 offset:0x1800
	ds_read_b64_tr_b16 v[236:237], v207 offset:0x2000
	ds_read_b64_tr_b16 v[238:239], v207 offset:0x2800
	ds_read_b64_tr_b16 v[240:241], v207 offset:0x3000
	ds_read_b64_tr_b16 v[242:243], v207 offset:0x3800
	s_nop 0
	s_waitcnt lgkmcnt(6)
; #define SBAR() __builtin_amdgcn_sched_barrier(0)
; __device__ __forceinline__ void partialSM(f32x16& p0, f32x16& p1, float& m_reg, float& mn, float& alpha) {
;     ...
;   float pmax = p0[0]; for (int r = 1; r < 16; ++r) pmax = fmaxf(pmax, p0[r]); for (int r = 0; r < 16; ++r) pmax = fmaxf(pmax, p1[r]);
;   { auto rr = __builtin_amdgcn_permlane32_swap(__float_as_uint(pmax), __float_as_uint(pmax), false, false);
;     pmax = fmaxf(__uint_as_float(rr[0]), __uint_as_float(rr[1])); }
;   if (__builtin_expect(__all(pmax - m_reg <= THR / SCALE), 1)) { mn = m_reg; alpha = 1.f; }
;   else { mn = fmaxf(m_reg, pmax); alpha = __builtin_amdgcn_exp2f((m_reg - mn) * C); m_reg = mn; }
; template <int OFF> __device__ __forceinline__ s16x4 tr_read(int vb) {
;   s16x4 r; asm volatile("ds_read_b64_tr_b16 %0, %1 offset:%2" : "=&v"(r) : "v"(vb), "i"(OFF) : "memory"); return r;
; }
; template <int D0> __device__ __forceinline__ void pv_one(f32x16& od, int vb, bf16x8 pa0, bf16x8 pa1, bf16x8 pa2, bf16x8 pa3) {
;   const s16x4 l0 = tr_read<v_rd_off(D0, 0, 0)>(vb), h0 = tr_read<v_rd_off(D0, 0, 1)>(vb), l1 = tr_read<v_rd_off(D0, 1, 0)>(vb), h1 = tr_read<v_rd_off(D0, 1, 1)>(vb);
;   const s16x4 l2 = tr_read<v_rd_off(D0, 2, 0)>(vb), h2 = tr_read<v_rd_off(D0, 2, 1)>(vb), l3 = tr_read<v_rd_off(D0, 3, 0)>(vb), h3 = tr_read<v_rd_off(D0, 3, 1)>(vb);
;   asm volatile("s_waitcnt lgkmcnt(0)" ::: "memory"); SBAR();
;     ...
;   od = __builtin_amdgcn_mfma_f32_32x32x16_bf16(pa0, PK(l0, h0), od, 0, 0, 0);
;   od = __builtin_amdgcn_mfma_f32_32x32x16_bf16(pa1, PK(l1, h1), od, 0, 0, 0);
;   od = __builtin_amdgcn_mfma_f32_32x32x16_bf16(pa2, PK(l2, h2), od, 0, 0, 0);
;   od = __builtin_amdgcn_mfma_f32_32x32x16_bf16(pa3, PK(l3, h3), od, 0, 0, 0);
;     ...
; }
; __device__ __forceinline__ void pv_d0(f32x16* o, int vb, bf16x8 pa0, bf16x8 pa1, bf16x8 pa2, bf16x8 pa3) {
;   pv_one<0>(o[0], vb, pa0, pa1, pa2, pa3); pv_one<1>(o[1], vb, pa0, pa1, pa2, pa3); pv_one<2>(o[2], vb, pa0, pa1, pa2, pa3); pv_one<3>(o[3], vb, pa0, pa1, pa2, pa3);
	v_mfma_f32_32x32x16_bf16 v[2:17], v[162:165], v[228:231], v[2:17]
	ds_read_b64_tr_b16 v[228:229], v207 offset:0x200
	ds_read_b64_tr_b16 v[230:231], v207 offset:0xa00
	s_waitcnt lgkmcnt(6)
	v_mfma_f32_32x32x16_bf16 v[2:17], v[166:169], v[232:235], v[2:17]
	ds_read_b64_tr_b16 v[232:233], v207 offset:0x1200
	ds_read_b64_tr_b16 v[234:235], v207 offset:0x1a00
	s_waitcnt lgkmcnt(6)
	v_mfma_f32_32x32x16_bf16 v[2:17], v[172:175], v[236:239], v[2:17]
	ds_read_b64_tr_b16 v[236:237], v207 offset:0x2200
	ds_read_b64_tr_b16 v[238:239], v207 offset:0x2a00
	s_waitcnt lgkmcnt(6)
	v_mfma_f32_32x32x16_bf16 v[2:17], v[224:227], v[240:243], v[2:17]
	ds_read_b64_tr_b16 v[240:241], v207 offset:0x3200
	ds_read_b64_tr_b16 v[242:243], v207 offset:0x3a00
	s_waitcnt lgkmcnt(6)
	v_mfma_f32_32x32x16_bf16 v[50:65], v[162:165], v[228:231], v[50:65]
	ds_read_b64_tr_b16 v[228:229], v207 offset:0x400
	ds_read_b64_tr_b16 v[230:231], v207 offset:0xc00
	s_waitcnt lgkmcnt(6)
	v_mfma_f32_32x32x16_bf16 v[50:65], v[166:169], v[232:235], v[50:65]
	ds_read_b64_tr_b16 v[232:233], v207 offset:0x1400
	ds_read_b64_tr_b16 v[234:235], v207 offset:0x1c00
	s_waitcnt lgkmcnt(6)
	v_mfma_f32_32x32x16_bf16 v[50:65], v[172:175], v[236:239], v[50:65]
	ds_read_b64_tr_b16 v[236:237], v207 offset:0x2400
	ds_read_b64_tr_b16 v[238:239], v207 offset:0x2c00
	s_waitcnt lgkmcnt(6)
	v_mfma_f32_32x32x16_bf16 v[50:65], v[224:227], v[240:243], v[50:65]
	ds_read_b64_tr_b16 v[240:241], v207 offset:0x3400
	ds_read_b64_tr_b16 v[242:243], v207 offset:0x3c00
	s_waitcnt lgkmcnt(6)
	v_mfma_f32_32x32x16_bf16 v[34:49], v[162:165], v[228:231], v[34:49]
	ds_read_b64_tr_b16 v[228:229], v207 offset:0x600
	ds_read_b64_tr_b16 v[230:231], v207 offset:0xe00
	s_waitcnt lgkmcnt(6)
	v_mfma_f32_32x32x16_bf16 v[34:49], v[166:169], v[232:235], v[34:49]
	ds_read_b64_tr_b16 v[232:233], v207 offset:0x1600
	ds_read_b64_tr_b16 v[234:235], v207 offset:0x1e00
	s_waitcnt lgkmcnt(6)
	v_mfma_f32_32x32x16_bf16 v[34:49], v[172:175], v[236:239], v[34:49]
	ds_read_b64_tr_b16 v[236:237], v207 offset:0x2600
	ds_read_b64_tr_b16 v[238:239], v207 offset:0x2e00
	s_waitcnt lgkmcnt(6)
	v_mfma_f32_32x32x16_bf16 v[34:49], v[224:227], v[240:243], v[34:49]
	ds_read_b64_tr_b16 v[240:241], v207 offset:0x3600
	ds_read_b64_tr_b16 v[242:243], v207 offset:0x3e00
	s_waitcnt lgkmcnt(6)
	v_mfma_f32_32x32x16_bf16 v[18:33], v[162:165], v[228:231], v[18:33]
	v_max_f32_e32 v162, v83, v83
	v_max_f32_e32 v163, v82, v82
	v_max_f32_e32 v162, v163, v162
	v_max3_f32 v162, v162, v84, v85
	v_max3_f32 v162, v162, v86, v87
	v_max3_f32 v162, v162, v88, v89
	v_max3_f32 v162, v162, v90, v91
	v_max3_f32 v162, v162, v92, v93
	v_max3_f32 v162, v162, v94, v95
	s_waitcnt lgkmcnt(4)
	v_mfma_f32_32x32x16_bf16 v[18:33], v[166:169], v[232:235], v[18:33]
	v_max3_f32 v162, v162, v96, v97
	v_max3_f32 v162, v162, v66, v67
	v_max3_f32 v162, v162, v68, v69
	v_max3_f32 v162, v162, v70, v71
	v_max3_f32 v162, v162, v72, v73
	v_max3_f32 v162, v162, v74, v75
	v_max3_f32 v162, v162, v76, v77
	v_max3_f32 v162, v162, v78, v79
	s_waitcnt lgkmcnt(2)
	v_mfma_f32_32x32x16_bf16 v[18:33], v[172:175], v[236:239], v[18:33]
	v_max3_f32 v162, v162, v80, v81
	v_mov_b32_e32 v163, v162
	s_nop 1
	v_permlane32_swap_b32_e32 v162, v163
	v_max_f32_e32 v163, v163, v163
	v_max_f32_e32 v162, v162, v162
	v_max_f32_e32 v162, v162, v163
	v_sub_f32_e32 v163, v162, v170
	v_cmp_ge_f32_e32 vcc, s27, v163
	v_max_f32_e32 v163, v170, v170
	v_max_f32_e32 v162, v163, v162
	s_waitcnt lgkmcnt(0)
	v_mfma_f32_32x32x16_bf16 v[18:33], v[224:227], v[240:243], v[18:33]
	v_sub_f32_e32 v163, v170, v162
	v_mul_f32_e32 v163, 0x3e0293ee, v163
	v_exp_f32_e32 v163, v163
	s_cmp_eq_u64 vcc, exec
	s_cselect_b64 s[0:1], -1, 0
	s_barrier
	s_waitcnt vmcnt(4)
	v_cndmask_b32_e64 v223, v163, 1.0, s[0:1]
	v_cmp_gt_f32_e32 vcc, 1.0, v223
	s_waitcnt vmcnt(7)
	ds_write_b128 v210, v[130:133]
	s_waitcnt vmcnt(6)
	ds_write_b128 v211, v[138:141]
	s_waitcnt vmcnt(5)
	ds_write_b128 v208, v[134:137] offset:32768
	s_waitcnt vmcnt(4)
	ds_write_b128 v209, v[142:145] offset:32768
	s_cbranch_vccz .LBB0_184
	s_and_saveexec_b64 s[44:45], s[40:41]
	ds_write_b32 v185, v223 offset:128
	s_or_b64 exec, exec, s[44:45]
	s_waitcnt lgkmcnt(0)
	v_add_u32_e32 v163, v181, v0
	ds_read_b128 v[164:167], v163 offset:224
	ds_read_b128 v[172:175], v163 offset:192
	ds_read_b128 v[224:227], v163 offset:160
	ds_read_b128 v[228:231], v163 offset:128
	s_waitcnt lgkmcnt(3)
	v_pk_mul_f32 v[14:15], v[14:15], v[164:165]
	s_waitcnt lgkmcnt(2)
	v_pk_mul_f32 v[10:11], v[10:11], v[172:173]
	s_waitcnt lgkmcnt(1)
	v_pk_mul_f32 v[6:7], v[6:7], v[224:225]
	v_pk_mul_f32 v[16:17], v[16:17], v[166:167]
	v_pk_mul_f32 v[12:13], v[12:13], v[174:175]
	v_pk_mul_f32 v[8:9], v[8:9], v[226:227]
	s_waitcnt lgkmcnt(0)
	v_pk_mul_f32 v[4:5], v[4:5], v[230:231]
	v_pk_mul_f32 v[2:3], v[2:3], v[228:229]
	v_pk_mul_f32 v[62:63], v[62:63], v[164:165]
	v_pk_mul_f32 v[58:59], v[58:59], v[172:173]
	v_pk_mul_f32 v[54:55], v[54:55], v[224:225]
	v_pk_mul_f32 v[64:65], v[64:65], v[166:167]
	v_pk_mul_f32 v[60:61], v[60:61], v[174:175]
	v_pk_mul_f32 v[56:57], v[56:57], v[226:227]
	v_pk_mul_f32 v[52:53], v[52:53], v[230:231]
	v_pk_mul_f32 v[50:51], v[50:51], v[228:229]
	v_pk_mul_f32 v[46:47], v[46:47], v[164:165]
	v_pk_mul_f32 v[42:43], v[42:43], v[172:173]
	v_pk_mul_f32 v[38:39], v[38:39], v[224:225]
	v_pk_mul_f32 v[48:49], v[48:49], v[166:167]
	v_pk_mul_f32 v[44:45], v[44:45], v[174:175]
	v_pk_mul_f32 v[40:41], v[40:41], v[226:227]
	v_pk_mul_f32 v[36:37], v[36:37], v[230:231]
	v_pk_mul_f32 v[34:35], v[34:35], v[228:229]
	v_pk_mul_f32 v[30:31], v[30:31], v[164:165]
	v_pk_mul_f32 v[26:27], v[26:27], v[172:173]
	v_pk_mul_f32 v[22:23], v[22:23], v[224:225]
	v_pk_mul_f32 v[32:33], v[32:33], v[166:167]
	v_pk_mul_f32 v[28:29], v[28:29], v[174:175]
	v_pk_mul_f32 v[24:25], v[24:25], v[226:227]
	v_pk_mul_f32 v[20:21], v[20:21], v[230:231]
	v_pk_mul_f32 v[18:19], v[18:19], v[228:229]

; #define SBAR() __builtin_amdgcn_sched_barrier(0)
; __device__ __forceinline__ void finishSM(f32x16& p0, f32x16& p1, float alpha, float& l_reg, bf16x8& pa0, bf16x8& pa1, bf16x8& pa2, bf16x8& pa3) {
;   for (int r = 0; r < 16; ++r) p1[r] = __builtin_amdgcn_exp2f(p1[r]);
;   float ps = 0; for (int r = 0; r < 16; ++r) ps += p0[r]; for (int r = 0; r < 16; ++r) ps += p1[r];
;   { auto rr = __builtin_amdgcn_permlane32_swap(__float_as_uint(ps), __float_as_uint(ps), false, false);
;     ps = __uint_as_float(rr[0]) + __uint_as_float(rr[1]); }
;   l_reg = l_reg * alpha + ps;
;     ...
;   PK4(p0, 0, pa0); PK4(p0, 8, pa1); PK4(p1, 0, pa2); PK4(p1, 8, pa3);
;     ...
; }
; __device__ __forceinline__ void qkt(f32x16& p0, f32x16& p1, const bf16* Ks, const bf16x8* qr, int r32, int hi) {
;   p0 = f32x16{}; p1 = f32x16{};
;   for (int d0 = 0; d0 < 8; ++d0) { int cb = (d0 * 16 + hi * 8) * 2;
;     bf16x8 b0 = *reinterpret_cast<const bf16x8*>((const char*)Ks + KSWZ(r32, cb));
;     bf16x8 b1 = *reinterpret_cast<const bf16x8*>((const char*)Ks + KSWZ(32 + r32, cb));
;     p0 = __builtin_amdgcn_mfma_f32_32x32x16_bf16(b0, qr[d0], p0, 0, 0, 0);
;     p1 = __builtin_amdgcn_mfma_f32_32x32x16_bf16(b1, qr[d0], p1, 0, 0, 0); }
; template <int OFF> __device__ __forceinline__ s16x4 tr_read(int vb) {
;   s16x4 r; asm volatile("ds_read_b64_tr_b16 %0, %1 offset:%2" : "=&v"(r) : "v"(vb), "i"(OFF) : "memory"); return r;
; }
; template <int D0> __device__ __forceinline__ void pv_one(f32x16& od, int vb, bf16x8 pa0, bf16x8 pa1, bf16x8 pa2, bf16x8 pa3) {
;   const s16x4 l0 = tr_read<v_rd_off(D0, 0, 0)>(vb), h0 = tr_read<v_rd_off(D0, 0, 1)>(vb), l1 = tr_read<v_rd_off(D0, 1, 0)>(vb), h1 = tr_read<v_rd_off(D0, 1, 1)>(vb);
;   const s16x4 l2 = tr_read<v_rd_off(D0, 2, 0)>(vb), h2 = tr_read<v_rd_off(D0, 2, 1)>(vb), l3 = tr_read<v_rd_off(D0, 3, 0)>(vb), h3 = tr_read<v_rd_off(D0, 3, 1)>(vb);
;   asm volatile("s_waitcnt lgkmcnt(0)" ::: "memory"); SBAR();
;     ...
;   od = __builtin_amdgcn_mfma_f32_32x32x16_bf16(pa0, PK(l0, h0), od, 0, 0, 0);
;   od = __builtin_amdgcn_mfma_f32_32x32x16_bf16(pa1, PK(l1, h1), od, 0, 0, 0);
;   od = __builtin_amdgcn_mfma_f32_32x32x16_bf16(pa2, PK(l2, h2), od, 0, 0, 0);
;   od = __builtin_amdgcn_mfma_f32_32x32x16_bf16(pa3, PK(l3, h3), od, 0, 0, 0);
.LBB0_192:
	ds_read_b128 v[66:69], v212 offset:49152
	ds_read_b128 v[70:73], v212 offset:57344
	s_waitcnt lgkmcnt(1)
	v_mfma_f32_32x32x16_bf16 v[82:97], v[66:69], v[118:121], 0
	s_waitcnt lgkmcnt(0)
	v_mfma_f32_32x32x16_bf16 v[66:81], v[70:73], v[118:121], 0
	ds_read_b128 v[118:121], v217 offset:49152
	ds_read_b128 v[130:133], v217 offset:57344
	s_waitcnt lgkmcnt(1)
	v_mfma_f32_32x32x16_bf16 v[82:97], v[118:121], v[110:113], v[82:97]
	s_waitcnt lgkmcnt(0)
	v_mfma_f32_32x32x16_bf16 v[66:81], v[130:133], v[110:113], v[66:81]
	ds_read_b128 v[110:113], v216 offset:49152
	ds_read_b128 v[118:121], v216 offset:57344
	s_waitcnt lgkmcnt(1)
	v_mfma_f32_32x32x16_bf16 v[82:97], v[110:113], v[126:129], v[82:97]
	s_waitcnt lgkmcnt(0)
	v_mfma_f32_32x32x16_bf16 v[66:81], v[118:121], v[126:129], v[66:81]
	ds_read_b128 v[110:113], v215 offset:49152
	ds_read_b128 v[118:121], v215 offset:57344
	s_waitcnt lgkmcnt(1)
	v_mfma_f32_32x32x16_bf16 v[82:97], v[110:113], v[122:125], v[82:97]
	s_waitcnt lgkmcnt(0)
	v_mfma_f32_32x32x16_bf16 v[66:81], v[118:121], v[122:125], v[66:81]
	ds_read_b128 v[110:113], v213 offset:49152
	ds_read_b128 v[118:121], v213 offset:57344
	v_exp_f32_e32 v122, v146
	v_exp_f32_e32 v123, v147
	s_waitcnt lgkmcnt(1)
	v_mfma_f32_32x32x16_bf16 v[82:97], v[110:113], v[114:117], v[82:97]
	s_waitcnt lgkmcnt(0)
	v_mfma_f32_32x32x16_bf16 v[66:81], v[118:121], v[114:117], v[66:81]
	ds_read_b128 v[110:113], v214 offset:49152
	ds_read_b128 v[114:117], v214 offset:57344
	v_exp_f32_e32 v118, v156
	v_exp_f32_e32 v119, v157
	v_exp_f32_e32 v120, v152
	v_exp_f32_e32 v121, v153
	s_waitcnt lgkmcnt(1)
	v_mfma_f32_32x32x16_bf16 v[82:97], v[110:113], v[106:109], v[82:97]
	s_waitcnt lgkmcnt(0)
	v_mfma_f32_32x32x16_bf16 v[66:81], v[114:117], v[106:109], v[66:81]
	ds_read_b128 v[106:109], v219 offset:49152
	ds_read_b128 v[110:113], v219 offset:57344
	v_exp_f32_e32 v114, v150
	v_exp_f32_e32 v115, v151
	v_exp_f32_e32 v116, v148
	v_exp_f32_e32 v117, v149
	s_waitcnt lgkmcnt(1)
	v_mfma_f32_32x32x16_bf16 v[82:97], v[106:109], v[102:105], v[82:97]
	s_waitcnt lgkmcnt(0)
	v_mfma_f32_32x32x16_bf16 v[66:81], v[110:113], v[102:105], v[66:81]
	ds_read_b128 v[102:105], v218 offset:49152
	ds_read_b128 v[106:109], v218 offset:57344
	v_exp_f32_e32 v110, v158
	v_exp_f32_e32 v111, v159
	v_exp_f32_e32 v112, v154
	v_exp_f32_e32 v113, v155
	s_waitcnt lgkmcnt(1)
	v_mfma_f32_32x32x16_bf16 v[82:97], v[102:105], v[98:101], v[82:97]
	s_waitcnt lgkmcnt(0)
	v_mfma_f32_32x32x16_bf16 v[66:81], v[106:109], v[98:101], v[66:81]
	v_add_f32_e32 v98, 0, v163
	v_add_f32_e32 v98, v177, v98
	v_add_f32_e32 v98, v164, v98
	v_add_f32_e32 v98, v224, v98
	v_add_f32_e32 v98, v176, v98
	v_add_f32_e32 v98, v227, v98
	v_add_f32_e32 v98, v165, v98
	v_add_f32_e32 v98, v175, v98
	v_add_f32_e32 v98, v166, v98
	v_add_f32_e32 v98, v173, v98
	v_add_f32_e32 v98, v167, v98
	v_add_f32_e32 v98, v174, v98
	v_exp_f32_e32 v108, v160
	v_add_f32_e32 v98, v168, v98
	v_exp_f32_e32 v109, v161
	v_add_f32_e32 v98, v171, v98
	v_add_f32_e32 v98, v169, v98
	v_add_f32_e32 v98, v172, v98
	v_add_f32_e32 v98, v108, v98
	v_add_f32_e32 v98, v109, v98
	v_add_f32_e32 v98, v110, v98
	v_add_f32_e32 v98, v111, v98
	v_add_f32_e32 v98, v112, v98
	v_add_f32_e32 v98, v113, v98
	v_add_f32_e32 v98, v114, v98
	v_add_f32_e32 v98, v115, v98
	v_add_f32_e32 v98, v116, v98
	v_add_f32_e32 v98, v117, v98
	v_add_f32_e32 v98, v118, v98
	v_add_f32_e32 v98, v119, v98
	v_add_f32_e32 v98, v120, v98
	v_add_f32_e32 v98, v121, v98
	v_add_f32_e32 v98, v122, v98
	v_add_f32_e32 v102, v123, v98
	v_mov_b32_e32 v103, v102
	v_cvt_pk_bf16_f32 v98, v163, v177
	v_cvt_pk_bf16_f32 v99, v164, v224
	v_cvt_pk_bf16_f32 v100, v176, v227
	v_cvt_pk_bf16_f32 v101, v165, v175
	s_nop 1
	v_permlane32_swap_b32_e32 v102, v103
	v_permlane32_swap_b32_e32 v98, v100
	v_permlane32_swap_b32_e32 v99, v101
	v_cvt_pk_bf16_f32 v104, v166, v173
	v_cvt_pk_bf16_f32 v105, v167, v174
	v_cvt_pk_bf16_f32 v106, v168, v171
	v_cvt_pk_bf16_f32 v107, v169, v172
	v_cvt_pk_bf16_f32 v108, v108, v109
	v_cvt_pk_bf16_f32 v109, v110, v111
	v_cvt_pk_bf16_f32 v110, v112, v113
	v_cvt_pk_bf16_f32 v111, v114, v115
	v_cvt_pk_bf16_f32 v112, v116, v117
	v_cvt_pk_bf16_f32 v113, v118, v119
	v_cvt_pk_bf16_f32 v114, v120, v121
	v_cvt_pk_bf16_f32 v115, v122, v123
	s_nop 0
	v_permlane32_swap_b32_e32 v104, v106
	v_permlane32_swap_b32_e32 v105, v107
	v_permlane32_swap_b32_e32 v108, v110
	v_permlane32_swap_b32_e32 v109, v111
	v_permlane32_swap_b32_e32 v112, v114
	v_permlane32_swap_b32_e32 v113, v115
	ds_read_b64_tr_b16 v[116:117], v207 offset:0
	ds_read_b64_tr_b16 v[118:119], v207 offset:0x800
	ds_read_b64_tr_b16 v[120:121], v207 offset:0x1000
	ds_read_b64_tr_b16 v[122:123], v207 offset:0x1800
	ds_read_b64_tr_b16 v[124:125], v207 offset:0x2000
	ds_read_b64_tr_b16 v[126:127], v207 offset:0x2800
	ds_read_b64_tr_b16 v[128:129], v207 offset:0x3000
	ds_read_b64_tr_b16 v[130:131], v207 offset:0x3800
	s_nop 0
	s_waitcnt lgkmcnt(6)
	v_mfma_f32_32x32x16_bf16 v[2:17], v[98:101], v[116:119], v[2:17]
	ds_read_b64_tr_b16 v[116:117], v207 offset:0x200
	ds_read_b64_tr_b16 v[118:119], v207 offset:0xa00
	s_waitcnt lgkmcnt(6)
	v_mfma_f32_32x32x16_bf16 v[2:17], v[104:107], v[120:123], v[2:17]
	ds_read_b64_tr_b16 v[120:121], v207 offset:0x1200
	ds_read_b64_tr_b16 v[122:123], v207 offset:0x1a00
	s_waitcnt lgkmcnt(6)
	v_mfma_f32_32x32x16_bf16 v[2:17], v[108:111], v[124:127], v[2:17]
	ds_read_b64_tr_b16 v[124:125], v207 offset:0x2200
	ds_read_b64_tr_b16 v[126:127], v207 offset:0x2a00
	s_waitcnt lgkmcnt(6)
	v_mfma_f32_32x32x16_bf16 v[2:17], v[112:115], v[128:131], v[2:17]
	ds_read_b64_tr_b16 v[128:129], v207 offset:0x3200
	ds_read_b64_tr_b16 v[130:131], v207 offset:0x3a00
	s_waitcnt lgkmcnt(6)
; #define SBAR() __builtin_amdgcn_sched_barrier(0)
; __device__ __forceinline__ void partialSM(f32x16& p0, f32x16& p1, float& m_reg, float& mn, float& alpha) {
;     ...
;   float pmax = p0[0]; for (int r = 1; r < 16; ++r) pmax = fmaxf(pmax, p0[r]); for (int r = 0; r < 16; ++r) pmax = fmaxf(pmax, p1[r]);
;   { auto rr = __builtin_amdgcn_permlane32_swap(__float_as_uint(pmax), __float_as_uint(pmax), false, false);
;     pmax = fmaxf(__uint_as_float(rr[0]), __uint_as_float(rr[1])); }
;   if (__builtin_expect(__all(pmax - m_reg <= THR / SCALE), 1)) { mn = m_reg; alpha = 1.f; }
;   else { mn = fmaxf(m_reg, pmax); alpha = __builtin_amdgcn_exp2f((m_reg - mn) * C); m_reg = mn; }
; template <int OFF> __device__ __forceinline__ s16x4 tr_read(int vb) {
;   s16x4 r; asm volatile("ds_read_b64_tr_b16 %0, %1 offset:%2" : "=&v"(r) : "v"(vb), "i"(OFF) : "memory"); return r;
; }
; template <int D0> __device__ __forceinline__ void pv_one(f32x16& od, int vb, bf16x8 pa0, bf16x8 pa1, bf16x8 pa2, bf16x8 pa3) {
;   const s16x4 l0 = tr_read<v_rd_off(D0, 0, 0)>(vb), h0 = tr_read<v_rd_off(D0, 0, 1)>(vb), l1 = tr_read<v_rd_off(D0, 1, 0)>(vb), h1 = tr_read<v_rd_off(D0, 1, 1)>(vb);
;   const s16x4 l2 = tr_read<v_rd_off(D0, 2, 0)>(vb), h2 = tr_read<v_rd_off(D0, 2, 1)>(vb), l3 = tr_read<v_rd_off(D0, 3, 0)>(vb), h3 = tr_read<v_rd_off(D0, 3, 1)>(vb);
;   asm volatile("s_waitcnt lgkmcnt(0)" ::: "memory"); SBAR();
;     ...
;   od = __builtin_amdgcn_mfma_f32_32x32x16_bf16(pa0, PK(l0, h0), od, 0, 0, 0);
;   od = __builtin_amdgcn_mfma_f32_32x32x16_bf16(pa1, PK(l1, h1), od, 0, 0, 0);
;   od = __builtin_amdgcn_mfma_f32_32x32x16_bf16(pa2, PK(l2, h2), od, 0, 0, 0);
;   od = __builtin_amdgcn_mfma_f32_32x32x16_bf16(pa3, PK(l3, h3), od, 0, 0, 0);
;     ...
; }
; __device__ __forceinline__ void pv_d0(f32x16* o, int vb, bf16x8 pa0, bf16x8 pa1, bf16x8 pa2, bf16x8 pa3) {
;   pv_one<0>(o[0], vb, pa0, pa1, pa2, pa3); pv_one<1>(o[1], vb, pa0, pa1, pa2, pa3); pv_one<2>(o[2], vb, pa0, pa1, pa2, pa3); pv_one<3>(o[3], vb, pa0, pa1, pa2, pa3);
	v_mfma_f32_32x32x16_bf16 v[50:65], v[98:101], v[116:119], v[50:65]
	ds_read_b64_tr_b16 v[116:117], v207 offset:0x400
	ds_read_b64_tr_b16 v[118:119], v207 offset:0xc00
	s_waitcnt lgkmcnt(6)
	v_mfma_f32_32x32x16_bf16 v[50:65], v[104:107], v[120:123], v[50:65]
	ds_read_b64_tr_b16 v[120:121], v207 offset:0x1400
	ds_read_b64_tr_b16 v[122:123], v207 offset:0x1c00
	s_waitcnt lgkmcnt(6)
	v_mfma_f32_32x32x16_bf16 v[50:65], v[108:111], v[124:127], v[50:65]
	ds_read_b64_tr_b16 v[124:125], v207 offset:0x2400
	ds_read_b64_tr_b16 v[126:127], v207 offset:0x2c00
	s_waitcnt lgkmcnt(6)
	v_mfma_f32_32x32x16_bf16 v[50:65], v[112:115], v[128:131], v[50:65]
	ds_read_b64_tr_b16 v[128:129], v207 offset:0x3400
	ds_read_b64_tr_b16 v[130:131], v207 offset:0x3c00
	s_waitcnt lgkmcnt(6)
	v_mfma_f32_32x32x16_bf16 v[34:49], v[98:101], v[116:119], v[34:49]
	ds_read_b64_tr_b16 v[116:117], v207 offset:0x600
	ds_read_b64_tr_b16 v[118:119], v207 offset:0xe00
	s_waitcnt lgkmcnt(6)
	v_mfma_f32_32x32x16_bf16 v[34:49], v[104:107], v[120:123], v[34:49]
	ds_read_b64_tr_b16 v[120:121], v207 offset:0x1600
	ds_read_b64_tr_b16 v[122:123], v207 offset:0x1e00
	s_waitcnt lgkmcnt(6)
	v_mfma_f32_32x32x16_bf16 v[34:49], v[108:111], v[124:127], v[34:49]
	ds_read_b64_tr_b16 v[124:125], v207 offset:0x2600
	ds_read_b64_tr_b16 v[126:127], v207 offset:0x2e00
	s_waitcnt lgkmcnt(6)
	v_mfma_f32_32x32x16_bf16 v[34:49], v[112:115], v[128:131], v[34:49]
	ds_read_b64_tr_b16 v[128:129], v207 offset:0x3600
	ds_read_b64_tr_b16 v[130:131], v207 offset:0x3e00
	s_waitcnt lgkmcnt(6)
	v_mfma_f32_32x32x16_bf16 v[18:33], v[98:101], v[116:119], v[18:33]
	v_max_f32_e32 v98, v83, v83
	v_max_f32_e32 v99, v82, v82
	v_max_f32_e32 v98, v99, v98
	v_max3_f32 v98, v98, v84, v85
	v_max3_f32 v98, v98, v86, v87
	v_max3_f32 v98, v98, v88, v89
	v_max3_f32 v98, v98, v90, v91
	v_max3_f32 v98, v98, v92, v93
	v_max3_f32 v98, v98, v94, v95
	s_waitcnt lgkmcnt(4)
	v_mfma_f32_32x32x16_bf16 v[18:33], v[104:107], v[120:123], v[18:33]
	v_max3_f32 v98, v98, v96, v97
	v_max3_f32 v98, v98, v66, v67
	v_max3_f32 v98, v98, v68, v69
	v_max3_f32 v98, v98, v70, v71
	v_max3_f32 v98, v98, v72, v73
	v_max3_f32 v98, v98, v74, v75
	v_max3_f32 v98, v98, v76, v77
	v_max3_f32 v98, v98, v78, v79
	s_waitcnt lgkmcnt(2)
	v_mfma_f32_32x32x16_bf16 v[18:33], v[108:111], v[124:127], v[18:33]
	v_max3_f32 v98, v98, v80, v81
	v_mov_b32_e32 v99, v98
	s_nop 1
	v_permlane32_swap_b32_e32 v98, v99
	v_max_f32_e32 v99, v99, v99
	v_max_f32_e32 v98, v98, v98
	v_max_f32_e32 v98, v98, v99
	v_sub_f32_e32 v99, v98, v170
	v_cmp_ge_f32_e32 vcc, s27, v99
	v_max_f32_e32 v99, v170, v170
	v_max_f32_e32 v99, v99, v98
	s_waitcnt lgkmcnt(0)
	v_mfma_f32_32x32x16_bf16 v[18:33], v[112:115], v[128:131], v[18:33]
	v_sub_f32_e32 v98, v170, v99
	v_mul_f32_e32 v98, 0x3e0293ee, v98
	v_exp_f32_e32 v98, v98
	s_cmp_eq_u64 vcc, exec
	s_cselect_b64 s[0:1], -1, 0
	v_cndmask_b32_e64 v98, v98, 1.0, s[0:1]
	v_cmp_gt_f32_e32 vcc, 1.0, v98
	s_barrier
	s_cbranch_vccz .LBB0_196
	s_and_saveexec_b64 s[44:45], s[40:41]
	ds_write_b32 v185, v98 offset:128
	s_or_b64 exec, exec, s[44:45]
	s_waitcnt lgkmcnt(0)
	v_add_u32_e32 v100, v181, v0
	ds_read_b128 v[104:107], v100 offset:224
	ds_read_b128 v[108:111], v100 offset:192
	ds_read_b128 v[112:115], v100 offset:160
	ds_read_b128 v[116:119], v100 offset:128
	s_waitcnt lgkmcnt(3)
	v_pk_mul_f32 v[14:15], v[14:15], v[104:105]
	s_waitcnt lgkmcnt(2)
	v_pk_mul_f32 v[10:11], v[10:11], v[108:109]
	s_waitcnt lgkmcnt(1)
	v_pk_mul_f32 v[6:7], v[6:7], v[112:113]
	v_pk_mul_f32 v[16:17], v[16:17], v[106:107]
	v_pk_mul_f32 v[12:13], v[12:13], v[110:111]
	v_pk_mul_f32 v[8:9], v[8:9], v[114:115]
	s_waitcnt lgkmcnt(0)
	v_pk_mul_f32 v[4:5], v[4:5], v[118:119]
	v_pk_mul_f32 v[2:3], v[2:3], v[116:117]
	v_pk_mul_f32 v[62:63], v[62:63], v[104:105]
	v_pk_mul_f32 v[58:59], v[58:59], v[108:109]
	v_pk_mul_f32 v[54:55], v[54:55], v[112:113]
	v_pk_mul_f32 v[64:65], v[64:65], v[106:107]
	v_pk_mul_f32 v[60:61], v[60:61], v[110:111]
	v_pk_mul_f32 v[56:57], v[56:57], v[114:115]
	v_pk_mul_f32 v[52:53], v[52:53], v[118:119]
	v_pk_mul_f32 v[50:51], v[50:51], v[116:117]
	v_pk_mul_f32 v[46:47], v[46:47], v[104:105]
	v_pk_mul_f32 v[42:43], v[42:43], v[108:109]
	v_pk_mul_f32 v[38:39], v[38:39], v[112:113]
	v_pk_mul_f32 v[48:49], v[48:49], v[106:107]
	v_pk_mul_f32 v[44:45], v[44:45], v[110:111]
	v_pk_mul_f32 v[40:41], v[40:41], v[114:115]
	v_pk_mul_f32 v[36:37], v[36:37], v[118:119]
	v_pk_mul_f32 v[34:35], v[34:35], v[116:117]
	v_pk_mul_f32 v[30:31], v[30:31], v[104:105]
	v_pk_mul_f32 v[26:27], v[26:27], v[108:109]
	v_pk_mul_f32 v[22:23], v[22:23], v[112:113]
	v_pk_mul_f32 v[32:33], v[32:33], v[106:107]
	v_pk_mul_f32 v[28:29], v[28:29], v[110:111]
	v_pk_mul_f32 v[24:25], v[24:25], v[114:115]
	v_pk_mul_f32 v[20:21], v[20:21], v[118:119]
	v_pk_mul_f32 v[18:19], v[18:19], v[116:117]
; #define SBAR() __builtin_amdgcn_sched_barrier(0)
; __device__ __forceinline__ void partialSM(f32x16& p0, f32x16& p1, float& m_reg, float& mn, float& alpha) {
;     ...
;   for (int r = 0; r < 16; ++r) p0[r] = fmaf(p0[r], C, mnC); for (int r = 0; r < 16; ++r) p1[r] = fmaf(p1[r], C, mnC);
;   for (int r = 0; r < 16; ++r) p0[r] = __builtin_amdgcn_exp2f(p0[r]);
; }
; __device__ __forceinline__ void finishSM(f32x16& p0, f32x16& p1, float alpha, float& l_reg, bf16x8& pa0, bf16x8& pa1, bf16x8& pa2, bf16x8& pa3) {
;   for (int r = 0; r < 16; ++r) p1[r] = __builtin_amdgcn_exp2f(p1[r]);
;   float ps = 0; for (int r = 0; r < 16; ++r) ps += p0[r]; for (int r = 0; r < 16; ++r) ps += p1[r];
;   { auto rr = __builtin_amdgcn_permlane32_swap(__float_as_uint(ps), __float_as_uint(ps), false, false);
;     ps = __uint_as_float(rr[0]) + __uint_as_float(rr[1]); }
;   l_reg = l_reg * alpha + ps;
;     ...
;   PK4(p0, 0, pa0); PK4(p0, 8, pa1); PK4(p1, 0, pa2); PK4(p1, 8, pa3);
; template <int OFF> __device__ __forceinline__ s16x4 tr_read(int vb) {
;   s16x4 r; asm volatile("ds_read_b64_tr_b16 %0, %1 offset:%2" : "=&v"(r) : "v"(vb), "i"(OFF) : "memory"); return r;
; }
; template <int D0> __device__ __forceinline__ void pv_one(f32x16& od, int vb, bf16x8 pa0, bf16x8 pa1, bf16x8 pa2, bf16x8 pa3) {
;   const s16x4 l0 = tr_read<v_rd_off(D0, 0, 0)>(vb), h0 = tr_read<v_rd_off(D0, 0, 1)>(vb), l1 = tr_read<v_rd_off(D0, 1, 0)>(vb), h1 = tr_read<v_rd_off(D0, 1, 1)>(vb);
;   const s16x4 l2 = tr_read<v_rd_off(D0, 2, 0)>(vb), h2 = tr_read<v_rd_off(D0, 2, 1)>(vb), l3 = tr_read<v_rd_off(D0, 3, 0)>(vb), h3 = tr_read<v_rd_off(D0, 3, 1)>(vb);
;   asm volatile("s_waitcnt lgkmcnt(0)" ::: "memory"); SBAR();
;     ...
;   od = __builtin_amdgcn_mfma_f32_32x32x16_bf16(pa0, PK(l0, h0), od, 0, 0, 0);
;   od = __builtin_amdgcn_mfma_f32_32x32x16_bf16(pa1, PK(l1, h1), od, 0, 0, 0);
;   od = __builtin_amdgcn_mfma_f32_32x32x16_bf16(pa2, PK(l2, h2), od, 0, 0, 0);
;   od = __builtin_amdgcn_mfma_f32_32x32x16_bf16(pa3, PK(l3, h3), od, 0, 0, 0);
;     ...
; }
; __device__ __forceinline__ void pv_d0(f32x16* o, int vb, bf16x8 pa0, bf16x8 pa1, bf16x8 pa2, bf16x8 pa3) {
;   pv_one<0>(o[0], vb, pa0, pa1, pa2, pa3); pv_one<1>(o[1], vb, pa0, pa1, pa2, pa3); pv_one<2>(o[2], vb, pa0, pa1, pa2, pa3); pv_one<3>(o[3], vb, pa0, pa1, pa2, pa3);
.LBB0_196:
	v_cndmask_b32_e64 v99, v99, v170, s[0:1]
	v_mul_f32_e32 v99, 0xbe0293ee, v99
	v_fmamk_f32 v82, v82, 0x3e0293ee, v99
	v_fmamk_f32 v83, v83, 0x3e0293ee, v99
	v_fmamk_f32 v100, v84, 0x3e0293ee, v99
	v_exp_f32_e32 v84, v82
	v_fmamk_f32 v101, v86, 0x3e0293ee, v99
	v_exp_f32_e32 v86, v83
	v_fmamk_f32 v85, v85, 0x3e0293ee, v99
	v_exp_f32_e32 v82, v100
	v_fmamk_f32 v66, v66, 0x3e0293ee, v99
	v_exp_f32_e32 v85, v85
	v_fmamk_f32 v104, v87, 0x3e0293ee, v99
	v_fmamk_f32 v113, v96, 0x3e0293ee, v99
	v_fmamk_f32 v96, v77, 0x3e0293ee, v99
	v_exp_f32_e32 v77, v101
	v_exp_f32_e32 v100, v66
	v_add_f32_e32 v66, 0, v84
	v_fmamk_f32 v105, v88, 0x3e0293ee, v99
	v_exp_f32_e32 v83, v104
	v_add_f32_e32 v66, v86, v66
	v_fmamk_f32 v106, v89, 0x3e0293ee, v99
	v_fmamk_f32 v112, v95, 0x3e0293ee, v99
	v_fmamk_f32 v95, v76, 0x3e0293ee, v99
	v_exp_f32_e32 v76, v105
	v_add_f32_e32 v66, v82, v66
	v_fmamk_f32 v107, v90, 0x3e0293ee, v99
	v_fmamk_f32 v114, v97, 0x3e0293ee, v99
	v_fmamk_f32 v97, v78, 0x3e0293ee, v99
	v_exp_f32_e32 v78, v106
	v_add_f32_e32 v66, v85, v66
	v_fmamk_f32 v108, v91, 0x3e0293ee, v99
	v_fmamk_f32 v109, v92, 0x3e0293ee, v99
	v_fmamk_f32 v92, v73, 0x3e0293ee, v99
	v_exp_f32_e32 v73, v107
	v_add_f32_e32 v66, v77, v66
	v_fmamk_f32 v111, v94, 0x3e0293ee, v99
	v_fmamk_f32 v94, v75, 0x3e0293ee, v99
	v_exp_f32_e32 v75, v108
	v_add_f32_e32 v66, v83, v66
	v_fmamk_f32 v110, v93, 0x3e0293ee, v99
	v_fmamk_f32 v90, v71, 0x3e0293ee, v99
	v_exp_f32_e32 v71, v109
	v_add_f32_e32 v66, v76, v66
	v_fmamk_f32 v93, v74, 0x3e0293ee, v99
	v_exp_f32_e32 v74, v110
	v_add_f32_e32 v66, v78, v66
	v_fmamk_f32 v88, v69, 0x3e0293ee, v99
	v_exp_f32_e32 v69, v111
	v_add_f32_e32 v66, v73, v66
	v_fmamk_f32 v91, v72, 0x3e0293ee, v99
	v_exp_f32_e32 v72, v112
	v_add_f32_e32 v66, v75, v66
	v_fmamk_f32 v87, v68, 0x3e0293ee, v99
	v_exp_f32_e32 v68, v113
	v_add_f32_e32 v66, v71, v66
	v_fmamk_f32 v89, v70, 0x3e0293ee, v99
	v_exp_f32_e32 v70, v114
	v_add_f32_e32 v66, v74, v66
	v_fmamk_f32 v67, v67, 0x3e0293ee, v99
	v_add_f32_e32 v66, v69, v66
	v_exp_f32_e32 v101, v67
	v_add_f32_e32 v66, v72, v66
	v_exp_f32_e32 v87, v87
	v_add_f32_e32 v66, v68, v66
	v_exp_f32_e32 v88, v88
	v_add_f32_e32 v66, v70, v66
	v_exp_f32_e32 v89, v89
	v_add_f32_e32 v66, v100, v66
	v_exp_f32_e32 v90, v90
	v_add_f32_e32 v66, v101, v66
	v_exp_f32_e32 v91, v91
	v_add_f32_e32 v66, v87, v66
	v_exp_f32_e32 v92, v92
	v_add_f32_e32 v66, v88, v66
	v_exp_f32_e32 v93, v93
	v_add_f32_e32 v66, v89, v66
	v_exp_f32_e32 v94, v94
	v_add_f32_e32 v66, v90, v66
	v_exp_f32_e32 v95, v95
	v_add_f32_e32 v66, v91, v66
	v_exp_f32_e32 v96, v96
	v_add_f32_e32 v66, v92, v66
	v_fmamk_f32 v79, v79, 0x3e0293ee, v99
	v_exp_f32_e32 v97, v97
	v_add_f32_e32 v66, v93, v66
	v_fmamk_f32 v80, v80, 0x3e0293ee, v99
	v_exp_f32_e32 v104, v79
	v_add_f32_e32 v66, v94, v66
	v_fmac_f32_e32 v99, 0x3e0293ee, v81
	v_exp_f32_e32 v105, v80
	v_add_f32_e32 v66, v95, v66
	v_exp_f32_e32 v99, v99
	v_add_f32_e32 v66, v96, v66
	v_add_f32_e32 v66, v97, v66
	v_add_f32_e32 v66, v104, v66
	v_add_f32_e32 v66, v105, v66
	v_add_f32_e32 v66, v99, v66
	v_mov_b32_e32 v67, v66
	s_nop 1
	v_permlane32_swap_b32_e32 v66, v67
	v_cvt_pk_bf16_f32 v80, v84, v86
	v_cvt_pk_bf16_f32 v81, v82, v85
	v_cvt_pk_bf16_f32 v82, v77, v83
	v_cvt_pk_bf16_f32 v83, v76, v78
	v_cvt_pk_bf16_f32 v76, v73, v75
	v_cvt_pk_bf16_f32 v77, v71, v74
	v_cvt_pk_bf16_f32 v78, v69, v72
	v_cvt_pk_bf16_f32 v79, v68, v70
	v_cvt_pk_bf16_f32 v68, v100, v101
	v_cvt_pk_bf16_f32 v69, v87, v88
	v_cvt_pk_bf16_f32 v70, v89, v90
	v_cvt_pk_bf16_f32 v71, v91, v92
	v_cvt_pk_bf16_f32 v72, v93, v94
	v_cvt_pk_bf16_f32 v73, v95, v96
	v_cvt_pk_bf16_f32 v74, v97, v104
	v_cvt_pk_bf16_f32 v75, v105, v99
	s_nop 0
	v_permlane32_swap_b32_e32 v80, v82
	v_permlane32_swap_b32_e32 v81, v83
	v_permlane32_swap_b32_e32 v76, v78
	v_permlane32_swap_b32_e32 v77, v79
	v_permlane32_swap_b32_e32 v68, v70
	v_permlane32_swap_b32_e32 v69, v71
	v_permlane32_swap_b32_e32 v72, v74
	v_permlane32_swap_b32_e32 v73, v75
	ds_read_b64_tr_b16 v[84:85], v187 offset:0
	ds_read_b64_tr_b16 v[86:87], v187 offset:0x800
	ds_read_b64_tr_b16 v[88:89], v187 offset:0x1000
	ds_read_b64_tr_b16 v[90:91], v187 offset:0x1800
	ds_read_b64_tr_b16 v[92:93], v187 offset:0x2000
	ds_read_b64_tr_b16 v[94:95], v187 offset:0x2800
	ds_read_b64_tr_b16 v[104:105], v187 offset:0x3000
	ds_read_b64_tr_b16 v[106:107], v187 offset:0x3800
	s_nop 0
	s_waitcnt lgkmcnt(6)
	v_mfma_f32_32x32x16_bf16 v[2:17], v[80:83], v[84:87], v[2:17]
	ds_read_b64_tr_b16 v[84:85], v187 offset:0x200
	ds_read_b64_tr_b16 v[86:87], v187 offset:0xa00
	s_waitcnt lgkmcnt(6)
	v_mfma_f32_32x32x16_bf16 v[2:17], v[76:79], v[88:91], v[2:17]
	ds_read_b64_tr_b16 v[88:89], v187 offset:0x1200
	ds_read_b64_tr_b16 v[90:91], v187 offset:0x1a00
	s_waitcnt lgkmcnt(6)
	v_mfma_f32_32x32x16_bf16 v[2:17], v[68:71], v[92:95], v[2:17]
	ds_read_b64_tr_b16 v[92:93], v187 offset:0x2200
	ds_read_b64_tr_b16 v[94:95], v187 offset:0x2a00
	s_waitcnt lgkmcnt(6)
	v_mfma_f32_32x32x16_bf16 v[2:17], v[72:75], v[104:107], v[2:17]
	ds_read_b64_tr_b16 v[104:105], v187 offset:0x3200
	ds_read_b64_tr_b16 v[106:107], v187 offset:0x3a00
	s_waitcnt lgkmcnt(6)
	v_mfma_f32_32x32x16_bf16 v[50:65], v[80:83], v[84:87], v[50:65]
	ds_read_b64_tr_b16 v[84:85], v187 offset:0x400
	ds_read_b64_tr_b16 v[86:87], v187 offset:0xc00
	s_waitcnt lgkmcnt(6)
	v_mfma_f32_32x32x16_bf16 v[50:65], v[76:79], v[88:91], v[50:65]
	ds_read_b64_tr_b16 v[88:89], v187 offset:0x1400
	ds_read_b64_tr_b16 v[90:91], v187 offset:0x1c00
	s_waitcnt lgkmcnt(6)
	v_mfma_f32_32x32x16_bf16 v[50:65], v[68:71], v[92:95], v[50:65]
	ds_read_b64_tr_b16 v[92:93], v187 offset:0x2400
	ds_read_b64_tr_b16 v[94:95], v187 offset:0x2c00
	s_waitcnt lgkmcnt(6)
	v_mfma_f32_32x32x16_bf16 v[50:65], v[72:75], v[104:107], v[50:65]
	ds_read_b64_tr_b16 v[104:105], v187 offset:0x3400
	ds_read_b64_tr_b16 v[106:107], v187 offset:0x3c00
	s_waitcnt lgkmcnt(6)
	v_mfma_f32_32x32x16_bf16 v[34:49], v[80:83], v[84:87], v[34:49]
	ds_read_b64_tr_b16 v[84:85], v187 offset:0x600
	ds_read_b64_tr_b16 v[86:87], v187 offset:0xe00
	s_waitcnt lgkmcnt(6)
	v_mfma_f32_32x32x16_bf16 v[34:49], v[76:79], v[88:91], v[34:49]
	ds_read_b64_tr_b16 v[88:89], v187 offset:0x1600
	ds_read_b64_tr_b16 v[90:91], v187 offset:0x1e00
	s_waitcnt lgkmcnt(6)
	v_mfma_f32_32x32x16_bf16 v[34:49], v[68:71], v[92:95], v[34:49]
	ds_read_b64_tr_b16 v[92:93], v187 offset:0x2600
	ds_read_b64_tr_b16 v[94:95], v187 offset:0x2e00
	s_waitcnt lgkmcnt(6)
	v_mfma_f32_32x32x16_bf16 v[34:49], v[72:75], v[104:107], v[34:49]
	ds_read_b64_tr_b16 v[104:105], v187 offset:0x3600
	ds_read_b64_tr_b16 v[106:107], v187 offset:0x3e00
	s_waitcnt lgkmcnt(6)
	v_mfma_f32_32x32x16_bf16 v[18:33], v[80:83], v[84:87], v[18:33]
	s_waitcnt lgkmcnt(4)
	v_mfma_f32_32x32x16_bf16 v[18:33], v[76:79], v[88:91], v[18:33]
	s_waitcnt lgkmcnt(2)
	v_mfma_f32_32x32x16_bf16 v[18:33], v[68:71], v[92:95], v[18:33]
	s_waitcnt lgkmcnt(0)
	v_mfma_f32_32x32x16_bf16 v[18:33], v[72:75], v[104:107], v[18:33]
	s_and_saveexec_b64 s[0:1], s[40:41]
	s_cbranch_execz .LBB0_174
; __device__ __forceinline__ void finishSM(f32x16& p0, f32x16& p1, float alpha, float& l_reg, bf16x8& pa0, bf16x8& pa1, bf16x8& pa2, bf16x8& pa3) {
;     ...
;   float ps = 0; for (int r = 0; r < 16; ++r) ps += p0[r]; for (int r = 0; r < 16; ++r) ps += p1[r];
;   { auto rr = __builtin_amdgcn_permlane32_swap(__float_as_uint(ps), __float_as_uint(ps), false, false);
;     ps = __uint_as_float(rr[0]) + __uint_as_float(rr[1]); }
;   l_reg = l_reg * alpha + ps;
; template <typename TQ>
; __device__ __forceinline__ void attn_dense_body(const TQ* __restrict__ Qb, const bf16* __restrict__ Kh, const bf16* __restrict__ Vh,
;                                                 bf16* __restrict__ Ob, int seq, char* lds) {
;     ...
;   if (hi == 0) li_l[r32] = l_reg; asm volatile("s_waitcnt lgkmcnt(0)" ::: "memory");
	v_add_f32_e32 v68, v102, v103
	v_fmac_f32_e32 v68, v186, v162
	v_add_f32_e32 v66, v66, v67
	v_fmac_f32_e32 v66, v68, v98
	ds_write_b32 v185, v66
	s_branch .LBB0_174
